# residual epilogues (out-proj, xa-out, ffn-out): first four residual-tile loads of the second row half issued right after the first half's loads into dead fragment registers
# speedup vs baseline: 1.0052x; 1.0052x over previous
; __device__ __forceinline__ unsigned char* launder(unsigned char* p) { unsigned long long v = (unsigned long long)p; asm volatile("" : "+s"(v)); return (unsigned char*)(GASP unsigned char*)v; }
;     __device__ __forceinline__ void operator()(const Acc& acc, const Unit& u, int wr, int wc, int fr, int fq) const {
;         unsigned char* ws = launder(ws_);
;         bf16_t* XB = (bf16_t*)(ws + WS_XB); float* ssn = ssidx >= 0 ? (float*)(ws + WS_SS) + (size_t)ssidx * M : nullptr;
; #pragma unroll
;         for (int ai = 0; ai < 2; ++ai) {
;             u32x4 xh[4][2];
; #pragma unroll
;             for (int m = 0; m < 4; ++m) {
;                 const size_t off = (size_t)(u.pm * 256 + ai * 128 + wr * 64 + m * 16 + fr) * 1024 + u.pn * 256 + 32 * wc + 8 * fq;
; #pragma unroll
;                 for (int bj = 0; bj < 2; ++bj) xh[m][bj] = *(const u32x4*)(XB + off + 128 * bj);
;             }
; #pragma unroll
;             for (int m = 0; m < 4; ++m) {
;                 const int row = u.pm * 256 + ai * 128 + wr * 64 + m * 16 + fr;
;                 const float f3 = fac ? fac[(ai * 128 + wr * 64 + m * 16 + fr) * 4 + 2] : 1.f;
;                 float ss = 0.f;
; #pragma unroll
;                 for (int bj = 0; bj < 2; ++bj) {
;                     const size_t off = (size_t)row * 1024 + u.pn * 256 + 128 * bj + 32 * wc + 8 * fq;
;                     float o[8];
; #pragma unroll
;                     for (int n = 0; n < 2; ++n)
; #pragma unroll
;                         for (int j = 0; j < 4; ++j) {
;                             const int e = 4 * n + j; const unsigned wh = xh[m][bj][e >> 1];
;                             const float v = ((e & 1) ? bfhi(wh) : bflo(wh)) + acc[ai][bj][m][n][j] * f3;
;                             o[e] = v; ss += v * v;
;                         }
;                     if (xfinal) { *(f32x4*)(xfinal + off) = (f32x4){o[0], o[1], o[2], o[3]}; *(f32x4*)(xfinal + off + 4) = (f32x4){o[4], o[5], o[6], o[7]}; }
;                     else st16(XB + off, o);
;                 }
;                 if (ssn) { ss += xshfl<16>(ss); ss += xshfl<32>(ss); if (fq == 0) atomicAdd(ssn + row, ss); }
;             }
.LBB0_764:
	s_mov_b64 s[28:29], s[2:3]
	s_add_u32 s24, s28, 0x4000000
	s_addc_u32 s25, s29, 0
	s_add_u32 s22, s28, s60
	s_addc_u32 s23, s29, 0
	v_lshl_add_u32 v180, s6, 8, v175
	s_lshl_b32 s6, s88, 8
	s_ashr_i32 s7, s6, 31
	s_lshl_b64 s[26:27], s[6:7], 1
	s_add_u32 s15, s24, s26
	s_addc_u32 s17, s25, s27
	s_add_u32 s26, s15, s61
	s_addc_u32 s27, s17, 0
	v_ashrrev_i32_e32 v181, 31, v180
	v_lshl_add_u64 v[184:185], s[26:27], 0, v[156:157]
	v_lshlrev_b64 v[208:209], 11, v[180:181]
	v_lshl_add_u64 v[128:129], v[184:185], 0, v[208:209]
	global_load_dwordx4 v[204:207], v[128:129], off
	global_load_dwordx4 v[152:155], v[128:129], off offset:256
	v_or_b32_e32 v128, 16, v180
	v_ashrrev_i32_e32 v129, 31, v128
	v_lshlrev_b64 v[190:191], 11, v[128:129]
	v_lshl_add_u64 v[128:129], v[184:185], 0, v[190:191]
	global_load_dwordx4 v[148:151], v[128:129], off
	global_load_dwordx4 v[144:147], v[128:129], off offset:256
	v_or_b32_e32 v128, 32, v180
	v_ashrrev_i32_e32 v129, 31, v128
	v_lshlrev_b64 v[188:189], 11, v[128:129]
	v_lshl_add_u64 v[128:129], v[184:185], 0, v[188:189]
	global_load_dwordx4 v[140:143], v[128:129], off
	global_load_dwordx4 v[136:139], v[128:129], off offset:256
	v_or_b32_e32 v128, 48, v180
	v_ashrrev_i32_e32 v129, 31, v128
	v_lshlrev_b64 v[186:187], 11, v[128:129]
	v_lshl_add_u64 v[128:129], v[184:185], 0, v[186:187]
	global_load_dwordx4 v[132:135], v[128:129], off
	s_nop 0
	global_load_dwordx4 v[128:131], v[128:129], off offset:256
	v_add_u32_e32 v234, 0x80, v180
	v_ashrrev_i32_e32 v235, 31, v234
	v_lshlrev_b64 v[238:239], 11, v[234:235]
	v_lshl_add_u64 v[234:235], v[184:185], 0, v[238:239]
	global_load_dwordx4 v[218:221], v[234:235], off
	global_load_dwordx4 v[222:225], v[234:235], off offset:256
	v_add_u32_e32 v234, 0x90, v180
	v_ashrrev_i32_e32 v235, 31, v234
	v_lshlrev_b64 v[236:237], 11, v[234:235]
	v_lshl_add_u64 v[234:235], v[184:185], 0, v[236:237]
	global_load_dwordx4 v[226:229], v[234:235], off
	global_load_dwordx4 v[230:233], v[234:235], off offset:256
	s_cmp_lg_u64 s[28:29], 0
	v_or_b32_e32 v182, s6, v174
	s_cselect_b64 s[26:27], -1, 0
	s_add_i32 s6, 0, 0x21000
	v_add_u32_e32 v203, s6, v201
	ds_read_b32 v210, v203 offset:8
	v_mov_b32_e32 v183, s7
	s_cmp_eq_u64 s[28:29], 0
	s_waitcnt vmcnt(4)
	v_lshlrev_b32_e32 v216, 16, v204
	v_and_b32_e32 v217, 0xffff0000, v204
	v_lshlrev_b32_e32 v204, 16, v205
	v_and_b32_e32 v205, 0xffff0000, v205
	s_waitcnt lgkmcnt(0)
	v_pk_fma_f32 v[122:123], v[122:123], v[210:211], v[204:205] op_sel_hi:[1,0,1]
	v_lshlrev_b32_e32 v204, 16, v206
	v_and_b32_e32 v205, 0xffff0000, v206
	v_pk_fma_f32 v[124:125], v[124:125], v[210:211], v[204:205] op_sel_hi:[1,0,1]
	v_lshlrev_b32_e32 v204, 16, v207
	v_and_b32_e32 v205, 0xffff0000, v207
	v_pk_fma_f32 v[120:121], v[120:121], v[210:211], v[216:217] op_sel_hi:[1,0,1]
	v_pk_fma_f32 v[126:127], v[126:127], v[210:211], v[204:205] op_sel_hi:[1,0,1]
	v_lshl_add_u64 v[204:205], s[24:25], 0, v[208:209]
	v_lshl_add_u64 v[208:209], v[182:183], 1, v[204:205]
	v_cvt_pk_bf16_f32 v204, v120, v121
	v_cvt_pk_bf16_f32 v205, v122, v123
	v_cvt_pk_bf16_f32 v206, v124, v125
	v_cvt_pk_bf16_f32 v207, v126, v127
	global_store_dwordx4 v[208:209], v[204:207], off
	s_nop 1
	v_lshlrev_b32_e32 v204, 16, v152
	v_and_b32_e32 v205, 0xffff0000, v152
	v_lshlrev_b32_e32 v152, 16, v153
	v_and_b32_e32 v153, 0xffff0000, v153
	v_pk_fma_f32 v[118:119], v[118:119], v[210:211], v[152:153] op_sel_hi:[1,0,1]
	v_lshlrev_b32_e32 v152, 16, v154
	v_and_b32_e32 v153, 0xffff0000, v154
	v_pk_fma_f32 v[112:113], v[112:113], v[210:211], v[152:153] op_sel_hi:[1,0,1]
	v_lshlrev_b32_e32 v152, 16, v155
	v_and_b32_e32 v153, 0xffff0000, v155
	v_pk_fma_f32 v[116:117], v[116:117], v[210:211], v[204:205] op_sel_hi:[1,0,1]
	v_pk_fma_f32 v[114:115], v[114:115], v[210:211], v[152:153] op_sel_hi:[1,0,1]
	v_cvt_pk_bf16_f32 v152, v116, v117
	v_cvt_pk_bf16_f32 v153, v118, v119
	v_cvt_pk_bf16_f32 v154, v112, v113
	v_cvt_pk_bf16_f32 v155, v114, v115
	global_store_dwordx4 v[208:209], v[152:155], off offset:256
	s_cbranch_scc1 .LBB0_768
	v_pk_mul_f32 v[120:121], v[120:121], v[120:121]
	v_pk_mul_f32 v[122:123], v[122:123], v[122:123]
	v_add_f32_e32 v120, v120, v121
	v_add_f32_e32 v120, v122, v120
	v_pk_mul_f32 v[124:125], v[124:125], v[124:125]
	v_add_f32_e32 v120, v123, v120
	v_add_f32_e32 v120, v124, v120
	v_pk_mul_f32 v[126:127], v[126:127], v[126:127]
	v_add_f32_e32 v120, v125, v120
	v_add_f32_e32 v120, v126, v120
	v_pk_mul_f32 v[116:117], v[116:117], v[116:117]
	v_add_f32_e32 v120, v127, v120
	v_add_f32_e32 v116, v116, v120
	v_pk_mul_f32 v[118:119], v[118:119], v[118:119]
	v_add_f32_e32 v116, v117, v116
	v_add_f32_e32 v116, v118, v116
	v_pk_mul_f32 v[112:113], v[112:113], v[112:113]
	v_add_f32_e32 v116, v119, v116
	v_add_f32_e32 v112, v112, v116
	v_pk_mul_f32 v[114:115], v[114:115], v[114:115]
	v_add_f32_e32 v112, v113, v112
	v_add_f32_e32 v112, v114, v112
	v_add_f32_e32 v112, v115, v112
	ds_swizzle_b32 v113, v112 offset:swizzle(SWAP,16)
	s_waitcnt lgkmcnt(0)
	v_add_f32_e32 v112, v112, v113
	v_mov_b32_e32 v113, v112
	v_mov_b32_e32 v114, v112
	s_nop 1
	v_permlane32_swap_b32_e32 v113, v114
	s_and_saveexec_b64 s[6:7], s[0:1]
	s_cbranch_execz .LBB0_767
	v_cmp_eq_u32_e32 vcc, 0, v214
	v_lshl_add_u64 v[116:117], v[180:181], 2, s[22:23]
	s_nop 0
	v_cndmask_b32_e32 v113, v113, v114, vcc
	v_add_f32_e32 v112, v112, v113
	global_atomic_add_f32 v[116:117], v112, off

;     __device__ __forceinline__ void operator()(const Acc& acc, const Unit& u, int wr, int wc, int fr, int fq) const {
;     ...
;             for (int m = 0; m < 4; ++m) {
;                 const size_t off = (size_t)(u.pm * 256 + ai * 128 + wr * 64 + m * 16 + fr) * 1024 + u.pn * 256 + 32 * wc + 8 * fq;
; #pragma unroll
;                 for (int bj = 0; bj < 2; ++bj) xh[m][bj] = *(const u32x4*)(XB + off + 128 * bj);
;             }
; #pragma unroll
;             for (int m = 0; m < 4; ++m) {
;                 const int row = u.pm * 256 + ai * 128 + wr * 64 + m * 16 + fr;
;                 const float f3 = fac ? fac[(ai * 128 + wr * 64 + m * 16 + fr) * 4 + 2] : 1.f;
;                 float ss = 0.f;
; #pragma unroll
;                 for (int bj = 0; bj < 2; ++bj) {
;                     const size_t off = (size_t)row * 1024 + u.pn * 256 + 128 * bj + 32 * wc + 8 * fq;
;                     float o[8];
; #pragma unroll
;                     for (int n = 0; n < 2; ++n)
; #pragma unroll
;                         for (int j = 0; j < 4; ++j) {
;                             const int e = 4 * n + j; const unsigned wh = xh[m][bj][e >> 1];
;                             const float v = ((e & 1) ? bfhi(wh) : bflo(wh)) + acc[ai][bj][m][n][j] * f3;
;                             o[e] = v; ss += v * v;
;                         }
;                     if (xfinal) { *(f32x4*)(xfinal + off) = (f32x4){o[0], o[1], o[2], o[3]}; *(f32x4*)(xfinal + off + 4) = (f32x4){o[4], o[5], o[6], o[7]}; }
;                     else st16(XB + off, o);
;                 }
;                 if (ssn) { ss += xshfl<16>(ss); ss += xshfl<32>(ss); if (fq == 0) atomicAdd(ssn + row, ss); }
;             }
.LBB0_780:
	s_waitcnt vmcnt(8)
	v_mov_b32_e32 v80, v230
	v_mov_b32_e32 v81, v231
	v_mov_b32_e32 v82, v232
	v_mov_b32_e32 v83, v233
	v_mov_b32_e32 v84, v226
	v_mov_b32_e32 v85, v227
	v_mov_b32_e32 v86, v228
	v_mov_b32_e32 v87, v229
	v_mov_b32_e32 v92, v236
	v_mov_b32_e32 v93, v237
	v_mov_b32_e32 v94, v218
	v_mov_b32_e32 v95, v219
	v_mov_b32_e32 v96, v220
	v_mov_b32_e32 v97, v221
	v_mov_b32_e32 v98, v222
	v_mov_b32_e32 v99, v223
	v_mov_b32_e32 v100, v224
	v_mov_b32_e32 v101, v225
	v_mov_b32_e32 v102, v238
	v_mov_b32_e32 v103, v239
	v_add_u32_e32 v64, 0xa0, v180
	v_ashrrev_i32_e32 v65, 31, v64
	v_lshlrev_b64 v[90:91], 11, v[64:65]
	v_lshl_add_u64 v[64:65], v[184:185], 0, v[90:91]
	global_load_dwordx4 v[76:79], v[64:65], off
	global_load_dwordx4 v[72:75], v[64:65], off offset:256
	v_add_u32_e32 v64, 0xb0, v180
	v_ashrrev_i32_e32 v65, 31, v64
	v_lshlrev_b64 v[88:89], 11, v[64:65]
	v_lshl_add_u64 v[64:65], v[184:185], 0, v[88:89]
	global_load_dwordx4 v[68:71], v[64:65], off
	s_nop 0
	global_load_dwordx4 v[64:67], v[64:65], off offset:256
	ds_read_b32 v104, v203 offset:2056
	s_and_b64 vcc, exec, s[6:7]
	s_waitcnt vmcnt(7)
	v_lshlrev_b32_e32 v106, 16, v94
	v_and_b32_e32 v107, 0xffff0000, v94
	v_lshlrev_b32_e32 v94, 16, v95
	v_and_b32_e32 v95, 0xffff0000, v95
	s_waitcnt lgkmcnt(0)
	v_pk_fma_f32 v[54:55], v[54:55], v[104:105], v[94:95] op_sel_hi:[1,0,1]
	v_lshlrev_b32_e32 v94, 16, v96
	v_and_b32_e32 v95, 0xffff0000, v96
	v_pk_fma_f32 v[48:49], v[48:49], v[104:105], v[94:95] op_sel_hi:[1,0,1]
	v_lshlrev_b32_e32 v94, 16, v97
	v_and_b32_e32 v95, 0xffff0000, v97
	v_pk_fma_f32 v[52:53], v[52:53], v[104:105], v[106:107] op_sel_hi:[1,0,1]
	v_pk_fma_f32 v[50:51], v[50:51], v[104:105], v[94:95] op_sel_hi:[1,0,1]
	v_lshl_add_u64 v[94:95], s[24:25], 0, v[102:103]
	v_lshl_add_u64 v[102:103], v[182:183], 1, v[94:95]
	v_cvt_pk_bf16_f32 v94, v52, v53
	v_cvt_pk_bf16_f32 v95, v54, v55
	v_cvt_pk_bf16_f32 v96, v48, v49
	v_cvt_pk_bf16_f32 v97, v50, v51
	global_store_dwordx4 v[102:103], v[94:97], off
	s_waitcnt vmcnt(7)
	s_nop 0
	v_lshlrev_b32_e32 v94, 16, v98
	v_and_b32_e32 v95, 0xffff0000, v98
	v_pk_fma_f32 v[60:61], v[60:61], v[104:105], v[94:95] op_sel_hi:[1,0,1]
	v_lshlrev_b32_e32 v94, 16, v99
	v_and_b32_e32 v95, 0xffff0000, v99
	v_pk_fma_f32 v[62:63], v[62:63], v[104:105], v[94:95] op_sel_hi:[1,0,1]
	v_lshlrev_b32_e32 v94, 16, v100
	v_and_b32_e32 v95, 0xffff0000, v100
	v_pk_fma_f32 v[56:57], v[56:57], v[104:105], v[94:95] op_sel_hi:[1,0,1]
	v_lshlrev_b32_e32 v94, 16, v101
	v_and_b32_e32 v95, 0xffff0000, v101
	v_pk_fma_f32 v[58:59], v[58:59], v[104:105], v[94:95] op_sel_hi:[1,0,1]
	v_cvt_pk_bf16_f32 v94, v60, v61
	v_cvt_pk_bf16_f32 v95, v62, v63
	v_cvt_pk_bf16_f32 v96, v56, v57
	v_cvt_pk_bf16_f32 v97, v58, v59
	global_store_dwordx4 v[102:103], v[94:97], off offset:256
	s_cbranch_vccnz .LBB0_784
	v_pk_mul_f32 v[52:53], v[52:53], v[52:53]
	v_pk_mul_f32 v[54:55], v[54:55], v[54:55]
	v_add_f32_e32 v52, v52, v53
	v_add_f32_e32 v52, v54, v52
	v_pk_mul_f32 v[48:49], v[48:49], v[48:49]
	v_add_f32_e32 v52, v55, v52
	v_add_f32_e32 v48, v48, v52
	v_pk_mul_f32 v[50:51], v[50:51], v[50:51]
	v_add_f32_e32 v48, v49, v48
	v_add_f32_e32 v48, v50, v48
	v_pk_mul_f32 v[60:61], v[60:61], v[60:61]
	v_add_f32_e32 v48, v51, v48
	v_add_f32_e32 v48, v60, v48
	v_pk_mul_f32 v[62:63], v[62:63], v[62:63]
	v_add_f32_e32 v48, v61, v48
	v_add_f32_e32 v48, v62, v48
	v_pk_mul_f32 v[56:57], v[56:57], v[56:57]
	v_add_f32_e32 v48, v63, v48
	v_add_f32_e32 v48, v56, v48
	v_pk_mul_f32 v[58:59], v[58:59], v[58:59]
	v_add_f32_e32 v48, v57, v48
	v_add_f32_e32 v48, v58, v48
	v_add_f32_e32 v48, v59, v48
	ds_swizzle_b32 v49, v48 offset:swizzle(SWAP,16)
	s_waitcnt lgkmcnt(0)
	v_add_f32_e32 v48, v48, v49
	v_mov_b32_e32 v49, v48
	v_mov_b32_e32 v50, v48
	s_nop 1
	v_permlane32_swap_b32_e32 v49, v50
	s_and_saveexec_b64 s[26:27], s[0:1]
	s_cbranch_execz .LBB0_783
	v_cmp_eq_u32_e32 vcc, 0, v214
	v_lshl_add_u64 v[52:53], v[180:181], 2, s[22:23]
	s_nop 0
	v_cndmask_b32_e32 v49, v49, v50, vcc
	v_add_f32_e32 v48, v48, v49
	global_atomic_add_f32 v[52:53], v48, off offset:512

; __device__ __forceinline__ unsigned char* launder(unsigned char* p) { unsigned long long v = (unsigned long long)p; asm volatile("" : "+s"(v)); return (unsigned char*)(GASP unsigned char*)v; }
;     __device__ __forceinline__ void operator()(const Acc& acc, const Unit& u, int wr, int wc, int fr, int fq) const {
;         unsigned char* ws = launder(ws_);
;         bf16_t* XB = (bf16_t*)(ws + WS_XB); float* ssn = ssidx >= 0 ? (float*)(ws + WS_SS) + (size_t)ssidx * M : nullptr;
; #pragma unroll
;         for (int ai = 0; ai < 2; ++ai) {
;             u32x4 xh[4][2];
; #pragma unroll
;             for (int m = 0; m < 4; ++m) {
;                 const size_t off = (size_t)(u.pm * 256 + ai * 128 + wr * 64 + m * 16 + fr) * 1024 + u.pn * 256 + 32 * wc + 8 * fq;
; #pragma unroll
;                 for (int bj = 0; bj < 2; ++bj) xh[m][bj] = *(const u32x4*)(XB + off + 128 * bj);
;             }
; #pragma unroll
;             for (int m = 0; m < 4; ++m) {
;                 const int row = u.pm * 256 + ai * 128 + wr * 64 + m * 16 + fr;
;                 const float f3 = fac ? fac[(ai * 128 + wr * 64 + m * 16 + fr) * 4 + 2] : 1.f;
;                 float ss = 0.f;
; #pragma unroll
;                 for (int bj = 0; bj < 2; ++bj) {
;                     const size_t off = (size_t)row * 1024 + u.pn * 256 + 128 * bj + 32 * wc + 8 * fq;
;                     float o[8];
; #pragma unroll
;                     for (int n = 0; n < 2; ++n)
; #pragma unroll
;                         for (int j = 0; j < 4; ++j) {
;                             const int e = 4 * n + j; const unsigned wh = xh[m][bj][e >> 1];
;                             const float v = ((e & 1) ? bfhi(wh) : bflo(wh)) + acc[ai][bj][m][n][j] * f3;
;                             o[e] = v; ss += v * v;
;                         }
;                     if (xfinal) { *(f32x4*)(xfinal + off) = (f32x4){o[0], o[1], o[2], o[3]}; *(f32x4*)(xfinal + off + 4) = (f32x4){o[4], o[5], o[6], o[7]}; }
;                     else st16(XB + off, o);
;                 }
;                 if (ssn) { ss += xshfl<16>(ss); ss += xshfl<32>(ss); if (fq == 0) atomicAdd(ssn + row, ss); }
;             }
.LBB0_1098:
	s_mov_b64 s[28:29], s[2:3]
	s_add_u32 s24, s28, 0x4000000
	s_addc_u32 s25, s29, 0
	s_add_u32 s22, s28, s57
	s_addc_u32 s23, s29, 0
	v_lshl_add_u32 v180, s6, 8, v175
	s_lshl_b32 s6, s59, 8
	s_ashr_i32 s7, s6, 31
	s_lshl_b64 s[26:27], s[6:7], 1
	s_add_u32 s15, s24, s26
	s_addc_u32 s17, s25, s27
	s_add_u32 s26, s15, s58
	s_addc_u32 s27, s17, 0
	v_ashrrev_i32_e32 v181, 31, v180
	v_lshl_add_u64 v[184:185], s[26:27], 0, v[156:157]
	v_lshlrev_b64 v[158:159], 11, v[180:181]
	v_lshl_add_u64 v[128:129], v[184:185], 0, v[158:159]
	global_load_dwordx4 v[194:197], v[128:129], off
	global_load_dwordx4 v[152:155], v[128:129], off offset:256
	v_or_b32_e32 v128, 16, v180
	v_ashrrev_i32_e32 v129, 31, v128
	v_lshlrev_b64 v[190:191], 11, v[128:129]
	v_lshl_add_u64 v[128:129], v[184:185], 0, v[190:191]
	global_load_dwordx4 v[148:151], v[128:129], off
	global_load_dwordx4 v[144:147], v[128:129], off offset:256
	v_or_b32_e32 v128, 32, v180
	v_ashrrev_i32_e32 v129, 31, v128
	v_lshlrev_b64 v[188:189], 11, v[128:129]
	v_lshl_add_u64 v[128:129], v[184:185], 0, v[188:189]
	global_load_dwordx4 v[140:143], v[128:129], off
	global_load_dwordx4 v[136:139], v[128:129], off offset:256
	v_or_b32_e32 v128, 48, v180
	v_ashrrev_i32_e32 v129, 31, v128
	v_lshlrev_b64 v[186:187], 11, v[128:129]
	v_lshl_add_u64 v[128:129], v[184:185], 0, v[186:187]
	global_load_dwordx4 v[132:135], v[128:129], off
	s_nop 0
	global_load_dwordx4 v[128:131], v[128:129], off offset:256
	v_add_u32_e32 v220, 0x80, v180
	v_ashrrev_i32_e32 v221, 31, v220
	v_lshlrev_b64 v[224:225], 11, v[220:221]
	v_lshl_add_u64 v[220:221], v[184:185], 0, v[224:225]
	global_load_dwordx4 v[200:203], v[220:221], off
	global_load_dwordx4 v[204:207], v[220:221], off offset:256
	v_add_u32_e32 v220, 0x90, v180
	v_ashrrev_i32_e32 v221, 31, v220
	v_lshlrev_b64 v[222:223], 11, v[220:221]
	v_lshl_add_u64 v[220:221], v[184:185], 0, v[222:223]
	global_load_dwordx4 v[208:211], v[220:221], off
	global_load_dwordx4 v[216:219], v[220:221], off offset:256
	v_mov_b32_e32 v183, s7
	v_or_b32_e32 v182, s6, v174
	v_lshl_add_u64 v[158:159], s[24:25], 0, v[158:159]
	v_lshl_add_u64 v[158:159], v[182:183], 1, v[158:159]
	s_cmp_lg_u64 s[28:29], 0
	s_cselect_b64 s[26:27], -1, 0
	s_cmp_eq_u64 s[28:29], 0
	s_waitcnt vmcnt(4)
	v_lshlrev_b32_e32 v198, 16, v194
	v_and_b32_e32 v199, 0xffff0000, v194
	v_lshlrev_b32_e32 v194, 16, v195
	v_and_b32_e32 v195, 0xffff0000, v195
	v_pk_add_f32 v[126:127], v[126:127], v[194:195]
	v_lshlrev_b32_e32 v194, 16, v196
	v_and_b32_e32 v195, 0xffff0000, v196
	v_pk_add_f32 v[120:121], v[120:121], v[194:195]
	v_lshlrev_b32_e32 v194, 16, v197
	v_and_b32_e32 v195, 0xffff0000, v197
	v_pk_add_f32 v[124:125], v[124:125], v[198:199]
	v_pk_add_f32 v[122:123], v[122:123], v[194:195]
	v_cvt_pk_bf16_f32 v194, v124, v125
	v_cvt_pk_bf16_f32 v195, v126, v127
	v_cvt_pk_bf16_f32 v196, v120, v121
	v_cvt_pk_bf16_f32 v197, v122, v123
	global_store_dwordx4 v[158:159], v[194:197], off
	s_nop 1
	v_lshlrev_b32_e32 v194, 16, v152
	v_and_b32_e32 v195, 0xffff0000, v152
	v_lshlrev_b32_e32 v152, 16, v153
	v_and_b32_e32 v153, 0xffff0000, v153
	v_pk_add_f32 v[118:119], v[118:119], v[152:153]
	v_lshlrev_b32_e32 v152, 16, v154
	v_and_b32_e32 v153, 0xffff0000, v154
	v_pk_add_f32 v[112:113], v[112:113], v[152:153]
	v_lshlrev_b32_e32 v152, 16, v155
	v_and_b32_e32 v153, 0xffff0000, v155
	v_pk_add_f32 v[116:117], v[116:117], v[194:195]
	v_pk_add_f32 v[114:115], v[114:115], v[152:153]
	v_cvt_pk_bf16_f32 v152, v116, v117
	v_cvt_pk_bf16_f32 v153, v118, v119
	v_cvt_pk_bf16_f32 v154, v112, v113
	v_cvt_pk_bf16_f32 v155, v114, v115
	global_store_dwordx4 v[158:159], v[152:155], off offset:256
	s_cbranch_scc1 .LBB0_1102
	v_pk_mul_f32 v[124:125], v[124:125], v[124:125]
	v_pk_mul_f32 v[126:127], v[126:127], v[126:127]
	v_add_f32_e32 v124, v124, v125
	v_add_f32_e32 v124, v126, v124
	v_pk_mul_f32 v[120:121], v[120:121], v[120:121]
	v_add_f32_e32 v124, v127, v124
	v_add_f32_e32 v120, v120, v124
	v_pk_mul_f32 v[122:123], v[122:123], v[122:123]
	v_add_f32_e32 v120, v121, v120
	v_add_f32_e32 v120, v122, v120
	v_pk_mul_f32 v[116:117], v[116:117], v[116:117]
	v_add_f32_e32 v120, v123, v120
	v_add_f32_e32 v116, v116, v120
	v_pk_mul_f32 v[118:119], v[118:119], v[118:119]
	v_add_f32_e32 v116, v117, v116
	v_add_f32_e32 v116, v118, v116
	v_pk_mul_f32 v[112:113], v[112:113], v[112:113]
	v_add_f32_e32 v116, v119, v116
	v_add_f32_e32 v112, v112, v116
	v_pk_mul_f32 v[114:115], v[114:115], v[114:115]
	v_add_f32_e32 v112, v113, v112
	v_add_f32_e32 v112, v114, v112
	v_add_f32_e32 v112, v115, v112
	ds_swizzle_b32 v113, v112 offset:swizzle(SWAP,16)
	s_waitcnt lgkmcnt(0)
	v_add_f32_e32 v112, v112, v113
	v_mov_b32_e32 v113, v112
	v_mov_b32_e32 v114, v112
	s_nop 1
	v_permlane32_swap_b32_e32 v113, v114
	s_and_saveexec_b64 s[6:7], s[0:1]
	s_cbranch_execz .LBB0_1101
	v_cmp_eq_u32_e32 vcc, 0, v214
	v_lshl_add_u64 v[116:117], v[180:181], 2, s[22:23]
	s_nop 0
	v_cndmask_b32_e32 v113, v113, v114, vcc
	v_add_f32_e32 v112, v112, v113
	global_atomic_add_f32 v[116:117], v112, off

;     __device__ __forceinline__ void operator()(const Acc& acc, const Unit& u, int wr, int wc, int fr, int fq) const {
;     ...
;             for (int m = 0; m < 4; ++m) {
;                 const size_t off = (size_t)(u.pm * 256 + ai * 128 + wr * 64 + m * 16 + fr) * 1024 + u.pn * 256 + 32 * wc + 8 * fq;
; #pragma unroll
;                 for (int bj = 0; bj < 2; ++bj) xh[m][bj] = *(const u32x4*)(XB + off + 128 * bj);
;             }
; #pragma unroll
;             for (int m = 0; m < 4; ++m) {
;                 const int row = u.pm * 256 + ai * 128 + wr * 64 + m * 16 + fr;
;                 const float f3 = fac ? fac[(ai * 128 + wr * 64 + m * 16 + fr) * 4 + 2] : 1.f;
;                 float ss = 0.f;
; #pragma unroll
;                 for (int bj = 0; bj < 2; ++bj) {
;                     const size_t off = (size_t)row * 1024 + u.pn * 256 + 128 * bj + 32 * wc + 8 * fq;
;                     float o[8];
; #pragma unroll
;                     for (int n = 0; n < 2; ++n)
; #pragma unroll
;                         for (int j = 0; j < 4; ++j) {
;                             const int e = 4 * n + j; const unsigned wh = xh[m][bj][e >> 1];
;                             const float v = ((e & 1) ? bfhi(wh) : bflo(wh)) + acc[ai][bj][m][n][j] * f3;
;                             o[e] = v; ss += v * v;
;                         }
;                     if (xfinal) { *(f32x4*)(xfinal + off) = (f32x4){o[0], o[1], o[2], o[3]}; *(f32x4*)(xfinal + off + 4) = (f32x4){o[4], o[5], o[6], o[7]}; }
;                     else st16(XB + off, o);
;                 }
;                 if (ssn) { ss += xshfl<16>(ss); ss += xshfl<32>(ss); if (fq == 0) atomicAdd(ssn + row, ss); }
;             }
.LBB0_1114:
	s_waitcnt vmcnt(8)
	v_mov_b32_e32 v80, v216
	v_mov_b32_e32 v81, v217
	v_mov_b32_e32 v82, v218
	v_mov_b32_e32 v83, v219
	v_mov_b32_e32 v84, v208
	v_mov_b32_e32 v85, v209
	v_mov_b32_e32 v86, v210
	v_mov_b32_e32 v87, v211
	v_mov_b32_e32 v92, v222
	v_mov_b32_e32 v93, v223
	v_mov_b32_e32 v94, v200
	v_mov_b32_e32 v95, v201
	v_mov_b32_e32 v96, v202
	v_mov_b32_e32 v97, v203
	v_mov_b32_e32 v98, v204
	v_mov_b32_e32 v99, v205
	v_mov_b32_e32 v100, v206
	v_mov_b32_e32 v101, v207
	v_mov_b32_e32 v102, v224
	v_mov_b32_e32 v103, v225
	v_add_u32_e32 v64, 0xa0, v180
	v_ashrrev_i32_e32 v65, 31, v64
	v_lshlrev_b64 v[90:91], 11, v[64:65]
	v_lshl_add_u64 v[64:65], v[184:185], 0, v[90:91]
	global_load_dwordx4 v[76:79], v[64:65], off
	global_load_dwordx4 v[72:75], v[64:65], off offset:256
	v_add_u32_e32 v64, 0xb0, v180
	v_ashrrev_i32_e32 v65, 31, v64
	v_lshlrev_b64 v[88:89], 11, v[64:65]
	v_lshl_add_u64 v[64:65], v[184:185], 0, v[88:89]
	global_load_dwordx4 v[68:71], v[64:65], off
	s_nop 0
	global_load_dwordx4 v[64:67], v[64:65], off offset:256
	s_and_b64 vcc, exec, s[6:7]
	s_waitcnt vmcnt(4)
	v_lshlrev_b32_e32 v104, 16, v94
	v_and_b32_e32 v105, 0xffff0000, v94
	v_lshlrev_b32_e32 v94, 16, v95
	v_and_b32_e32 v95, 0xffff0000, v95
	v_pk_add_f32 v[62:63], v[62:63], v[94:95]
	v_lshlrev_b32_e32 v94, 16, v96
	v_and_b32_e32 v95, 0xffff0000, v96
	v_pk_add_f32 v[56:57], v[56:57], v[94:95]
	v_lshlrev_b32_e32 v94, 16, v97
	v_and_b32_e32 v95, 0xffff0000, v97
	v_pk_add_f32 v[60:61], v[60:61], v[104:105]
	v_pk_add_f32 v[58:59], v[58:59], v[94:95]
	v_lshl_add_u64 v[94:95], s[24:25], 0, v[102:103]
	v_lshl_add_u64 v[102:103], v[182:183], 1, v[94:95]
	v_cvt_pk_bf16_f32 v94, v60, v61
	v_cvt_pk_bf16_f32 v95, v62, v63
	v_cvt_pk_bf16_f32 v96, v56, v57
	v_cvt_pk_bf16_f32 v97, v58, v59
	global_store_dwordx4 v[102:103], v[94:97], off
	s_nop 1
	v_lshlrev_b32_e32 v94, 16, v98
	v_and_b32_e32 v95, 0xffff0000, v98
	v_pk_add_f32 v[52:53], v[52:53], v[94:95]
	v_lshlrev_b32_e32 v94, 16, v99
	v_and_b32_e32 v95, 0xffff0000, v99
	v_pk_add_f32 v[54:55], v[54:55], v[94:95]
	v_lshlrev_b32_e32 v94, 16, v100
	v_and_b32_e32 v95, 0xffff0000, v100
	v_pk_add_f32 v[48:49], v[48:49], v[94:95]
	v_lshlrev_b32_e32 v94, 16, v101
	v_and_b32_e32 v95, 0xffff0000, v101
	v_pk_add_f32 v[50:51], v[50:51], v[94:95]
	v_cvt_pk_bf16_f32 v94, v52, v53
	v_cvt_pk_bf16_f32 v95, v54, v55
	v_cvt_pk_bf16_f32 v96, v48, v49
	v_cvt_pk_bf16_f32 v97, v50, v51
	global_store_dwordx4 v[102:103], v[94:97], off offset:256
	s_cbranch_vccnz .LBB0_1118
	v_pk_mul_f32 v[60:61], v[60:61], v[60:61]
	v_pk_mul_f32 v[62:63], v[62:63], v[62:63]
	v_add_f32_e32 v60, v60, v61
	v_add_f32_e32 v60, v62, v60
	v_pk_mul_f32 v[56:57], v[56:57], v[56:57]
	v_add_f32_e32 v60, v63, v60
	v_add_f32_e32 v56, v56, v60
	v_pk_mul_f32 v[58:59], v[58:59], v[58:59]
	v_add_f32_e32 v56, v57, v56
	v_add_f32_e32 v56, v58, v56
	v_pk_mul_f32 v[52:53], v[52:53], v[52:53]
	v_add_f32_e32 v56, v59, v56
	v_add_f32_e32 v52, v52, v56
	v_pk_mul_f32 v[54:55], v[54:55], v[54:55]
	v_add_f32_e32 v52, v53, v52
	v_add_f32_e32 v52, v54, v52
	v_pk_mul_f32 v[48:49], v[48:49], v[48:49]
	v_add_f32_e32 v52, v55, v52
	v_add_f32_e32 v48, v48, v52
	v_pk_mul_f32 v[50:51], v[50:51], v[50:51]
	v_add_f32_e32 v48, v49, v48
	v_add_f32_e32 v48, v50, v48
	v_add_f32_e32 v48, v51, v48
	ds_swizzle_b32 v49, v48 offset:swizzle(SWAP,16)
	s_waitcnt lgkmcnt(0)
	v_add_f32_e32 v48, v48, v49
	v_mov_b32_e32 v49, v48
	v_mov_b32_e32 v50, v48
	s_nop 1
	v_permlane32_swap_b32_e32 v49, v50
	s_and_saveexec_b64 s[26:27], s[0:1]
	s_cbranch_execz .LBB0_1117
	v_cmp_eq_u32_e32 vcc, 0, v214
	v_lshl_add_u64 v[52:53], v[180:181], 2, s[22:23]
	s_nop 0
	v_cndmask_b32_e32 v49, v49, v50, vcc
	v_add_f32_e32 v48, v48, v49
	global_atomic_add_f32 v[52:53], v48, off offset:512

;     __device__ __forceinline__ void operator()(const Acc& acc, const Unit& u, int wr, int wc, int fr, int fq) const {
;     ...
; #pragma unroll
;             for (int m = 0; m < 4; ++m) {
;                 const int row = u.pm * 256 + ai * 128 + wr * 64 + m * 16 + fr;
;                 const float f3 = fac ? fac[(ai * 128 + wr * 64 + m * 16 + fr) * 4 + 2] : 1.f;
;                 float ss = 0.f;
; #pragma unroll
;                 for (int bj = 0; bj < 2; ++bj) {
;                     const size_t off = (size_t)row * 1024 + u.pn * 256 + 128 * bj + 32 * wc + 8 * fq;
;                     float o[8];
; #pragma unroll
;                     for (int n = 0; n < 2; ++n)
; #pragma unroll
;                         for (int j = 0; j < 4; ++j) {
;                             const int e = 4 * n + j; const unsigned wh = xh[m][bj][e >> 1];
;                             const float v = ((e & 1) ? bfhi(wh) : bflo(wh)) + acc[ai][bj][m][n][j] * f3;
;                             o[e] = v; ss += v * v;
;                         }
;                     if (xfinal) { *(f32x4*)(xfinal + off) = (f32x4){o[0], o[1], o[2], o[3]}; *(f32x4*)(xfinal + off + 4) = (f32x4){o[4], o[5], o[6], o[7]}; }
;                     else st16(XB + off, o);
;                 }
;                 if (ssn) { ss += xshfl<16>(ss); ss += xshfl<32>(ss); if (fq == 0) atomicAdd(ssn + row, ss); }
.LBB0_1122:
	s_waitcnt vmcnt(4)
	v_lshlrev_b32_e32 v32, 16, v76
	v_and_b32_e32 v33, 0xffff0000, v76
	v_pk_add_f32 v[28:29], v[28:29], v[32:33]
	v_lshlrev_b32_e32 v32, 16, v77
	v_and_b32_e32 v33, 0xffff0000, v77
	v_pk_add_f32 v[30:31], v[30:31], v[32:33]
	v_lshlrev_b32_e32 v32, 16, v78
	v_and_b32_e32 v33, 0xffff0000, v78
	v_pk_add_f32 v[24:25], v[24:25], v[32:33]
	v_lshlrev_b32_e32 v32, 16, v79
	v_and_b32_e32 v33, 0xffff0000, v79
	v_pk_add_f32 v[26:27], v[26:27], v[32:33]
	v_lshl_add_u64 v[32:33], s[24:25], 0, v[90:91]
	v_lshl_add_u64 v[36:37], v[182:183], 1, v[32:33]
	v_cvt_pk_bf16_f32 v32, v28, v29
	v_cvt_pk_bf16_f32 v33, v30, v31
	v_cvt_pk_bf16_f32 v34, v24, v25
	v_cvt_pk_bf16_f32 v35, v26, v27
	global_store_dwordx4 v[36:37], v[32:35], off
	s_and_b64 vcc, exec, s[6:7]
	s_nop 0
	v_lshlrev_b32_e32 v32, 16, v72
	v_and_b32_e32 v33, 0xffff0000, v72
	v_pk_add_f32 v[20:21], v[20:21], v[32:33]
	v_lshlrev_b32_e32 v32, 16, v73
	v_and_b32_e32 v33, 0xffff0000, v73
	v_pk_add_f32 v[22:23], v[22:23], v[32:33]
	v_lshlrev_b32_e32 v32, 16, v74
	v_and_b32_e32 v33, 0xffff0000, v74
	v_pk_add_f32 v[16:17], v[16:17], v[32:33]
	v_lshlrev_b32_e32 v32, 16, v75
	v_and_b32_e32 v33, 0xffff0000, v75
	v_pk_add_f32 v[18:19], v[18:19], v[32:33]
	v_cvt_pk_bf16_f32 v32, v20, v21
	v_cvt_pk_bf16_f32 v33, v22, v23
	v_cvt_pk_bf16_f32 v34, v16, v17
	v_cvt_pk_bf16_f32 v35, v18, v19
	global_store_dwordx4 v[36:37], v[32:35], off offset:256
	s_cbranch_vccnz .LBB0_1126
	v_pk_mul_f32 v[28:29], v[28:29], v[28:29]
	v_pk_mul_f32 v[30:31], v[30:31], v[30:31]
	v_add_f32_e32 v28, v28, v29
	v_add_f32_e32 v28, v30, v28
	v_pk_mul_f32 v[24:25], v[24:25], v[24:25]
	v_add_f32_e32 v28, v31, v28
	v_add_f32_e32 v24, v24, v28
	v_pk_mul_f32 v[26:27], v[26:27], v[26:27]
	v_add_f32_e32 v24, v25, v24
	v_add_f32_e32 v24, v26, v24
	v_pk_mul_f32 v[20:21], v[20:21], v[20:21]
	v_add_f32_e32 v24, v27, v24
	v_add_f32_e32 v20, v20, v24
	v_pk_mul_f32 v[22:23], v[22:23], v[22:23]
	v_add_f32_e32 v20, v21, v20
	v_add_f32_e32 v20, v22, v20
	v_pk_mul_f32 v[16:17], v[16:17], v[16:17]
	v_add_f32_e32 v20, v23, v20
	v_add_f32_e32 v16, v16, v20
	v_pk_mul_f32 v[18:19], v[18:19], v[18:19]
	v_add_f32_e32 v16, v17, v16
	v_add_f32_e32 v16, v18, v16
	v_add_f32_e32 v16, v19, v16
	ds_swizzle_b32 v17, v16 offset:swizzle(SWAP,16)
	s_waitcnt lgkmcnt(0)
	v_add_f32_e32 v16, v16, v17
	v_mov_b32_e32 v17, v16
	v_mov_b32_e32 v18, v16
	s_nop 1
	v_permlane32_swap_b32_e32 v17, v18
	s_and_saveexec_b64 s[26:27], s[0:1]
	s_cbranch_execz .LBB0_1125
	v_cmp_eq_u32_e32 vcc, 0, v214
	v_lshl_add_u64 v[20:21], v[180:181], 2, s[22:23]
	s_nop 0
	v_cndmask_b32_e32 v17, v17, v18, vcc
	v_add_f32_e32 v16, v16, v17
	global_atomic_add_f32 v[20:21], v16, off offset:640

; __device__ __forceinline__ unsigned char* launder(unsigned char* p) { unsigned long long v = (unsigned long long)p; asm volatile("" : "+s"(v)); return (unsigned char*)(GASP unsigned char*)v; }
;     __device__ __forceinline__ void operator()(const Acc& acc, const Unit& u, int wr, int wc, int fr, int fq) const {
;         unsigned char* ws = launder(ws_);
;         bf16_t* XB = (bf16_t*)(ws + WS_XB); float* ssn = ssidx >= 0 ? (float*)(ws + WS_SS) + (size_t)ssidx * M : nullptr;
; #pragma unroll
;         for (int ai = 0; ai < 2; ++ai) {
;             u32x4 xh[4][2];
; #pragma unroll
;             for (int m = 0; m < 4; ++m) {
;                 const size_t off = (size_t)(u.pm * 256 + ai * 128 + wr * 64 + m * 16 + fr) * 1024 + u.pn * 256 + 32 * wc + 8 * fq;
; #pragma unroll
;                 for (int bj = 0; bj < 2; ++bj) xh[m][bj] = *(const u32x4*)(XB + off + 128 * bj);
;             }
; #pragma unroll
;             for (int m = 0; m < 4; ++m) {
;                 const int row = u.pm * 256 + ai * 128 + wr * 64 + m * 16 + fr;
;                 const float f3 = fac ? fac[(ai * 128 + wr * 64 + m * 16 + fr) * 4 + 2] : 1.f;
;                 float ss = 0.f;
; #pragma unroll
;                 for (int bj = 0; bj < 2; ++bj) {
;                     const size_t off = (size_t)row * 1024 + u.pn * 256 + 128 * bj + 32 * wc + 8 * fq;
;                     float o[8];
; #pragma unroll
;                     for (int n = 0; n < 2; ++n)
; #pragma unroll
;                         for (int j = 0; j < 4; ++j) {
;                             const int e = 4 * n + j; const unsigned wh = xh[m][bj][e >> 1];
;                             const float v = ((e & 1) ? bfhi(wh) : bflo(wh)) + acc[ai][bj][m][n][j] * f3;
;                             o[e] = v; ss += v * v;
;                         }
;                     if (xfinal) { *(f32x4*)(xfinal + off) = (f32x4){o[0], o[1], o[2], o[3]}; *(f32x4*)(xfinal + off + 4) = (f32x4){o[4], o[5], o[6], o[7]}; }
.LBB0_1379:
	s_mov_b64 s[8:9], s[2:3]
	s_add_u32 s26, s8, 0x4000000
	s_addc_u32 s27, s9, 0
	s_lshl_b32 s6, s88, 8
	s_ashr_i32 s7, s6, 31
	s_lshl_b64 s[28:29], s[6:7], 1
	s_add_u32 s28, s26, s28
	s_addc_u32 s29, s27, s29
	v_lshl_add_u32 v180, s61, 8, v175
	s_add_u32 s28, s28, s58
	s_addc_u32 s29, s29, 0
	v_ashrrev_i32_e32 v181, 31, v180
	v_lshl_add_u64 v[184:185], s[28:29], 0, v[156:157]
	v_lshlrev_b64 v[128:129], 11, v[180:181]
	v_or_b32_e32 v190, 16, v180
	v_lshl_add_u64 v[128:129], v[184:185], 0, v[128:129]
	v_ashrrev_i32_e32 v191, 31, v190
	global_load_dwordx4 v[198:201], v[128:129], off
	global_load_dwordx4 v[152:155], v[128:129], off offset:256
	v_lshlrev_b64 v[128:129], 11, v[190:191]
	v_or_b32_e32 v188, 32, v180
	v_lshl_add_u64 v[128:129], v[184:185], 0, v[128:129]
	v_ashrrev_i32_e32 v189, 31, v188
	global_load_dwordx4 v[148:151], v[128:129], off
	global_load_dwordx4 v[144:147], v[128:129], off offset:256
	v_lshlrev_b64 v[128:129], 11, v[188:189]
	v_or_b32_e32 v186, 48, v180
	v_lshl_add_u64 v[128:129], v[184:185], 0, v[128:129]
	v_ashrrev_i32_e32 v187, 31, v186
	global_load_dwordx4 v[140:143], v[128:129], off
	global_load_dwordx4 v[136:139], v[128:129], off offset:256
	v_lshlrev_b64 v[128:129], 11, v[186:187]
	v_lshl_add_u64 v[128:129], v[184:185], 0, v[128:129]
	global_load_dwordx4 v[132:135], v[128:129], off
	s_nop 0
	global_load_dwordx4 v[128:131], v[128:129], off offset:256
	v_add_u32_e32 v228, 0x80, v180
	v_ashrrev_i32_e32 v229, 31, v228
	v_lshlrev_b64 v[210:211], 11, v[228:229]
	v_add_u32_e32 v226, 0x90, v180
	v_lshl_add_u64 v[210:211], v[184:185], 0, v[210:211]
	v_ashrrev_i32_e32 v227, 31, v226
	global_load_dwordx4 v[202:205], v[210:211], off
	global_load_dwordx4 v[206:209], v[210:211], off offset:256
	v_lshlrev_b64 v[210:211], 11, v[226:227]
	v_add_u32_e32 v224, 0xa0, v180
	v_lshl_add_u64 v[210:211], v[184:185], 0, v[210:211]
	v_ashrrev_i32_e32 v225, 31, v224
	global_load_dwordx4 v[216:219], v[210:211], off
	global_load_dwordx4 v[220:223], v[210:211], off offset:256
	v_mov_b32_e32 v183, s7
	v_or_b32_e32 v182, s6, v174
	v_lshlrev_b64 v[158:159], 10, v[180:181]
	v_lshl_add_u64 v[192:193], v[158:159], 0, v[182:183]
	s_andn2_b64 vcc, exec, s[20:21]
	v_lshl_add_u64 v[194:195], v[192:193], 2, s[10:11]
	s_waitcnt vmcnt(4)
	v_lshlrev_b32_e32 v158, 16, v198
	v_and_b32_e32 v159, 0xffff0000, v198
	v_pk_add_f32 v[124:125], v[124:125], v[158:159]
	v_lshlrev_b32_e32 v158, 16, v199
	v_and_b32_e32 v159, 0xffff0000, v199
	v_pk_add_f32 v[126:127], v[126:127], v[158:159]
	v_lshlrev_b32_e32 v158, 16, v200
	v_and_b32_e32 v159, 0xffff0000, v200
	v_pk_add_f32 v[120:121], v[120:121], v[158:159]
	v_lshlrev_b32_e32 v158, 16, v201
	v_and_b32_e32 v159, 0xffff0000, v201
	v_pk_add_f32 v[122:123], v[122:123], v[158:159]
	v_cndmask_b32_e64 v158, 0, 1, s[20:21]
	v_cmp_ne_u32_e64 s[6:7], 1, v158
	s_cbranch_vccnz .LBB0_1462
	global_store_dwordx4 v[194:195], v[124:127], off
	global_store_dwordx4 v[194:195], v[120:123], off offset:16
	s_cbranch_execnz .LBB0_1382

;     __device__ __forceinline__ void operator()(const Acc& acc, const Unit& u, int wr, int wc, int fr, int fq) const {
;     ...
;             for (int m = 0; m < 4; ++m) {
;                 const size_t off = (size_t)(u.pm * 256 + ai * 128 + wr * 64 + m * 16 + fr) * 1024 + u.pn * 256 + 32 * wc + 8 * fq;
; #pragma unroll
;                 for (int bj = 0; bj < 2; ++bj) xh[m][bj] = *(const u32x4*)(XB + off + 128 * bj);
;             }
; #pragma unroll
;             for (int m = 0; m < 4; ++m) {
;                 const int row = u.pm * 256 + ai * 128 + wr * 64 + m * 16 + fr;
;                 const float f3 = fac ? fac[(ai * 128 + wr * 64 + m * 16 + fr) * 4 + 2] : 1.f;
;                 float ss = 0.f;
; #pragma unroll
;                 for (int bj = 0; bj < 2; ++bj) {
;                     const size_t off = (size_t)row * 1024 + u.pn * 256 + 128 * bj + 32 * wc + 8 * fq;
;                     float o[8];
; #pragma unroll
;                     for (int n = 0; n < 2; ++n)
; #pragma unroll
;                         for (int j = 0; j < 4; ++j) {
;                             const int e = 4 * n + j; const unsigned wh = xh[m][bj][e >> 1];
;                             const float v = ((e & 1) ? bfhi(wh) : bflo(wh)) + acc[ai][bj][m][n][j] * f3;
;                             o[e] = v; ss += v * v;
;                         }
;                     if (xfinal) { *(f32x4*)(xfinal + off) = (f32x4){o[0], o[1], o[2], o[3]}; *(f32x4*)(xfinal + off + 4) = (f32x4){o[4], o[5], o[6], o[7]}; }
.LBB0_1419:
	s_waitcnt vmcnt(8)
	v_mov_b32_e32 v80, v220
	v_mov_b32_e32 v81, v221
	v_mov_b32_e32 v82, v222
	v_mov_b32_e32 v83, v223
	v_mov_b32_e32 v84, v216
	v_mov_b32_e32 v85, v217
	v_mov_b32_e32 v86, v218
	v_mov_b32_e32 v87, v219
	v_mov_b32_e32 v88, v206
	v_mov_b32_e32 v89, v207
	v_mov_b32_e32 v90, v208
	v_mov_b32_e32 v91, v209
	v_mov_b32_e32 v94, v224
	v_mov_b32_e32 v95, v225
	v_mov_b32_e32 v96, v226
	v_mov_b32_e32 v97, v227
	v_mov_b32_e32 v98, v228
	v_mov_b32_e32 v99, v229
	v_mov_b32_e32 v100, v202
	v_mov_b32_e32 v101, v203
	v_mov_b32_e32 v102, v204
	v_mov_b32_e32 v103, v205
	v_lshlrev_b64 v[64:65], 11, v[94:95]
	v_add_u32_e32 v92, 0xb0, v180
	v_lshl_add_u64 v[64:65], v[184:185], 0, v[64:65]
	v_ashrrev_i32_e32 v93, 31, v92
	global_load_dwordx4 v[76:79], v[64:65], off
	global_load_dwordx4 v[72:75], v[64:65], off offset:256
	v_lshlrev_b64 v[64:65], 11, v[92:93]
	v_lshl_add_u64 v[64:65], v[184:185], 0, v[64:65]
	global_load_dwordx4 v[68:71], v[64:65], off
	s_nop 0
	global_load_dwordx4 v[64:67], v[64:65], off offset:256
	v_lshlrev_b64 v[98:99], 10, v[98:99]
	v_lshl_add_u64 v[98:99], v[98:99], 0, v[182:183]
	s_and_b64 vcc, exec, s[6:7]
	s_waitcnt vmcnt(4)
	v_lshlrev_b32_e32 v104, 16, v100
	v_and_b32_e32 v105, 0xffff0000, v100
	v_lshlrev_b32_e32 v100, 16, v101
	v_and_b32_e32 v101, 0xffff0000, v101
	v_pk_add_f32 v[62:63], v[62:63], v[100:101]
	v_lshlrev_b32_e32 v100, 16, v102
	v_and_b32_e32 v101, 0xffff0000, v102
	v_pk_add_f32 v[56:57], v[56:57], v[100:101]
	v_lshlrev_b32_e32 v100, 16, v103
	v_and_b32_e32 v101, 0xffff0000, v103
	v_pk_add_f32 v[60:61], v[60:61], v[104:105]
	v_pk_add_f32 v[58:59], v[58:59], v[100:101]
	v_lshl_add_u64 v[100:101], v[98:99], 2, s[10:11]
	s_cbranch_vccnz .LBB0_1470
	global_store_dwordx4 v[100:101], v[60:63], off
	global_store_dwordx4 v[100:101], v[56:59], off offset:16
	s_cbranch_execnz .LBB0_1422

;     __device__ __forceinline__ void operator()(const Acc& acc, const Unit& u, int wr, int wc, int fr, int fq) const {
;     ...
; #pragma unroll
;             for (int m = 0; m < 4; ++m) {
;                 const int row = u.pm * 256 + ai * 128 + wr * 64 + m * 16 + fr;
;                 const float f3 = fac ? fac[(ai * 128 + wr * 64 + m * 16 + fr) * 4 + 2] : 1.f;
;                 float ss = 0.f;
; #pragma unroll
;                 for (int bj = 0; bj < 2; ++bj) {
;                     const size_t off = (size_t)row * 1024 + u.pn * 256 + 128 * bj + 32 * wc + 8 * fq;
;                     float o[8];
; #pragma unroll
;                     for (int n = 0; n < 2; ++n)
; #pragma unroll
;                         for (int j = 0; j < 4; ++j) {
;                             const int e = 4 * n + j; const unsigned wh = xh[m][bj][e >> 1];
;                             const float v = ((e & 1) ? bfhi(wh) : bflo(wh)) + acc[ai][bj][m][n][j] * f3;
;                             o[e] = v; ss += v * v;
;                         }
;                     if (xfinal) { *(f32x4*)(xfinal + off) = (f32x4){o[0], o[1], o[2], o[3]}; *(f32x4*)(xfinal + off + 4) = (f32x4){o[4], o[5], o[6], o[7]}; }
.LBB0_1439:
	s_waitcnt vmcnt(4)
	v_lshlrev_b32_e32 v34, 16, v76
	v_and_b32_e32 v35, 0xffff0000, v76
	v_pk_add_f32 v[28:29], v[28:29], v[34:35]
	v_lshlrev_b32_e32 v34, 16, v77
	v_and_b32_e32 v35, 0xffff0000, v77
	v_lshlrev_b64 v[32:33], 10, v[94:95]
	v_pk_add_f32 v[30:31], v[30:31], v[34:35]
	v_lshlrev_b32_e32 v34, 16, v78
	v_and_b32_e32 v35, 0xffff0000, v78
	v_lshl_add_u64 v[32:33], v[32:33], 0, v[182:183]
	v_pk_add_f32 v[24:25], v[24:25], v[34:35]
	v_lshlrev_b32_e32 v34, 16, v79
	v_and_b32_e32 v35, 0xffff0000, v79
	v_pk_add_f32 v[26:27], v[26:27], v[34:35]
	s_and_b64 vcc, exec, s[6:7]
	v_lshl_add_u64 v[34:35], v[32:33], 2, s[10:11]
	s_cbranch_vccnz .LBB0_1474
	global_store_dwordx4 v[34:35], v[28:31], off
	global_store_dwordx4 v[34:35], v[24:27], off offset:16
	s_cbranch_execnz .LBB0_1442
